# work-table retune: last-round compensation 60 (sums 226/282)
# speedup vs baseline: 1.0017x; 1.0017x over previous
_ZL6NSA_QB:
	.byte	127, 48, 47, 4, 126, 49, 46, 5, 125, 50, 45, 6, 124, 51, 44, 7, 123, 52, 43, 8, 122, 53, 42, 9, 121, 54, 41, 10, 120, 55, 40, 11, 119, 56, 39, 12, 118, 57, 38, 13, 117, 58, 37, 14, 116, 59, 36, 15, 115, 76, 35, 0, 114, 77, 34, 1, 113, 78, 33, 2, 112, 79, 32, 3, 111, 80, 31, 60, 110, 81, 30, 61, 109, 82, 29, 62, 108, 83, 28, 63, 107, 84, 27, 64, 106, 85, 26, 65, 105, 86, 25, 66, 104, 87, 24, 67, 103, 88, 23, 68, 102, 89, 22, 69, 101, 90, 21, 70, 100, 91, 20, 71, 99, 92, 19, 72, 98, 93, 18, 73, 97, 94, 17, 74, 96, 95, 16, 75
	.size	_ZL6NSA_QB, 128

	.type	__hip_cuid_aaa9f4bcd633d1df,@object
